# seams before FFN-down/GLU/W_out/W_o: idle waves touch the first weight tile's first two K-tiles so its first LDS-DMA hits L2
# speedup vs baseline: 1.0117x; 1.0012x over previous
; __device__ __forceinline__ void xcd_barrier(const XcdBarrier& b) {
;     asm volatile("s_waitcnt vmcnt(0)" ::: "memory");
;     __syncthreads();
.LBB0_231:
	s_cmp_gt_i32 s31, 2
	s_cselect_b64 s[0:1], -1, 0
	s_and_b64 s[4:5], s[6:7], s[0:1]
	s_andn2_b64 vcc, exec, s[4:5]
	s_cbranch_vccnz .LBB0_285
	s_waitcnt vmcnt(0)
	s_waitcnt vmcnt(0) lgkmcnt(0)
	s_barrier
	v_readlane_b32 s100, v249, 18
	s_nop 3
	s_cmp_eq_u32 s100, 0
	s_cbranch_scc1 .Lwarm_done_0
	s_lshr_b32 s101, s92, 9
	s_and_b32 s101, s101, 3
	s_mul_i32 s101, s101, 0x160000
	s_add_u32 s98, s28, 0x3400000
	s_addc_u32 s99, s29, 0
	s_add_u32 s98, s98, s101
	s_addc_u32 s99, s99, 0
	v_lshrrev_b32_e32 v250, 1, v196
	v_lshl_add_u32 v250, s100, 5, v250
	v_mul_u32_u24_e32 v250, 0x1600, v250
	v_and_b32_e32 v251, 1, v196
	v_lshl_add_u32 v250, v251, 7, v250
	global_load_dword v250, v250, s[98:99]

; __device__ __forceinline__ void xcd_barrier(const XcdBarrier& b) {
;     asm volatile("s_waitcnt vmcnt(0)" ::: "memory");
;     __syncthreads();
; __global__ void __launch_bounds__(NTHREADS, 2) mega_fwd(Args a) {
;     ...
;     if (IN(6)) { EpiGlu E{YB, a.in[20], CAT}; run_gemm(lds, YB, (const bf16_t*)(ws + WS_WGLU), T, 512, 512, E); }
.LBB0_552:
	s_cmp_gt_i32 s31, 6
	s_cselect_b64 s[4:5], -1, 0
	s_and_b64 s[6:7], s[48:49], s[4:5]
	s_andn2_b64 vcc, exec, s[6:7]
	s_cbranch_vccnz .LBB0_606
	s_waitcnt vmcnt(0)
	s_waitcnt vmcnt(0) lgkmcnt(0)
	s_barrier
	v_readlane_b32 s100, v249, 18
	s_nop 3
	s_cmp_eq_u32 s100, 0
	s_cbranch_scc1 .Lwarm_done_1
	s_lshr_b32 s101, s92, 9
	s_and_b32 s101, s101, 1
	s_mul_i32 s101, s101, 0x40000
	s_add_u32 s98, s28, 0x4d00000
	s_addc_u32 s99, s29, 0
	s_add_u32 s98, s98, s101
	s_addc_u32 s99, s99, 0
	v_lshrrev_b32_e32 v250, 1, v196
	v_lshl_add_u32 v250, s100, 5, v250
	v_mul_u32_u24_e32 v250, 0x400, v250
	v_and_b32_e32 v251, 1, v196
	v_lshl_add_u32 v250, v251, 7, v250
	global_load_dword v250, v250, s[98:99]

; __device__ __forceinline__ void xcd_barrier(const XcdBarrier& b) {
;     asm volatile("s_waitcnt vmcnt(0)" ::: "memory");
;     __syncthreads();
; __global__ void __launch_bounds__(NTHREADS, 2) mega_fwd(Args a) {
;     ...
;     if (IN(7)) { EpiResid E{XB, 1.f, SS + 2 * SSN}; run_gemm(lds, CAT, (const bf16_t*)(ws + WS_WOUT), T, D, D, E); }
.LBB0_631:
	s_cmp_gt_i32 s31, 7
	s_cselect_b64 s[0:1], -1, 0
	s_and_b64 s[4:5], s[6:7], s[0:1]
	s_andn2_b64 vcc, exec, s[4:5]
	s_cbranch_vccnz .LBB0_685
	s_waitcnt vmcnt(0)
	s_waitcnt vmcnt(0) lgkmcnt(0)
	s_barrier
	v_readlane_b32 s100, v249, 18
	s_nop 3
	s_cmp_eq_u32 s100, 0
	s_cbranch_scc1 .Lwarm_done_2
	s_lshr_b32 s101, s92, 9
	s_and_b32 s101, s101, 3
	s_mul_i32 s101, s101, 0x80000
	s_add_u32 s98, s28, 0x4e00000
	s_addc_u32 s99, s29, 0
	s_add_u32 s98, s98, s101
	s_addc_u32 s99, s99, 0
	v_lshrrev_b32_e32 v250, 1, v196
	v_lshl_add_u32 v250, s100, 5, v250
	v_mul_u32_u24_e32 v250, 0x800, v250
	v_and_b32_e32 v251, 1, v196
	v_lshl_add_u32 v250, v251, 7, v250
	global_load_dword v250, v250, s[98:99]

; __device__ __forceinline__ void xcd_barrier(const XcdBarrier& b) {
;     asm volatile("s_waitcnt vmcnt(0)" ::: "memory");
;     __syncthreads();
.LBB0_817:
	s_cmp_gt_i32 s31, 9
	s_cselect_b64 s[0:1], -1, 0
	s_and_b64 s[4:5], s[6:7], s[0:1]
	s_andn2_b64 vcc, exec, s[4:5]
	s_cbranch_vccnz .LBB0_871
	s_waitcnt vmcnt(0)
	s_waitcnt vmcnt(0) lgkmcnt(0)
	s_barrier
	v_readlane_b32 s100, v249, 18
	s_nop 3
	s_cmp_eq_u32 s100, 0
	s_cbranch_scc1 .Lwarm_done_3
	s_lshr_b32 s101, s92, 9
	s_and_b32 s101, s101, 3
	s_mul_i32 s101, s101, 0x160000
	s_add_u32 s98, s28, 0x3980000
	s_addc_u32 s99, s29, 0
	s_add_u32 s98, s98, s101
	s_addc_u32 s99, s99, 0
	v_lshrrev_b32_e32 v250, 1, v196
	v_lshl_add_u32 v250, s100, 5, v250
	v_mul_u32_u24_e32 v250, 0x1600, v250
	v_and_b32_e32 v251, 1, v196
	v_lshl_add_u32 v250, v251, 7, v250
	global_load_dword v250, v250, s[98:99]

; __device__ __forceinline__ void xcd_barrier(const XcdBarrier& b) {
;     asm volatile("s_waitcnt vmcnt(0)" ::: "memory");
;     __syncthreads();
.LBB0_1007:
	s_cmp_gt_i32 s31, 11
	s_cselect_b64 s[0:1], -1, 0
	s_and_b64 s[4:5], s[6:7], s[0:1]
	s_andn2_b64 vcc, exec, s[4:5]
	s_cbranch_vccnz .LBB0_1061
	s_waitcnt vmcnt(0)
	s_waitcnt vmcnt(0) lgkmcnt(0)
	s_barrier
	v_readlane_b32 s100, v249, 18
	s_nop 3
	s_cmp_eq_u32 s100, 0
	s_cbranch_scc1 .Lwarm_done_4
	s_lshr_b32 s101, s92, 9
	s_and_b32 s101, s101, 3
	s_mul_i32 s101, s101, 0x160000
	s_add_u32 s98, s28, 0x3f00000
	s_addc_u32 s99, s29, 0
	s_add_u32 s98, s98, s101
	s_addc_u32 s99, s99, 0
	v_lshrrev_b32_e32 v250, 1, v196
	v_lshl_add_u32 v250, s100, 5, v250
	v_mul_u32_u24_e32 v250, 0x1600, v250
	v_and_b32_e32 v251, 1, v196
	v_lshl_add_u32 v250, v251, 7, v250
	global_load_dword v250, v250, s[98:99]

; __device__ __forceinline__ void xcd_barrier(const XcdBarrier& b) {
;     asm volatile("s_waitcnt vmcnt(0)" ::: "memory");
;     __syncthreads();
; __global__ void __launch_bounds__(NTHREADS, 2) mega_fwd(Args a) {
;     ...
;     if (IN(15)) { EpiResid E{XB, 1.f, SS + 5 * SSN}; run_gemm(lds, OA, (const bf16_t*)(ws + WS_WO), T, D, D, E); }
.LBB0_1561:
	s_cmp_gt_i32 s31, 15
	s_cselect_b64 s[0:1], -1, 0
	s_and_b64 s[4:5], s[38:39], s[0:1]
	s_andn2_b64 vcc, exec, s[4:5]
	s_cbranch_vccnz .LBB0_1615
	s_waitcnt vmcnt(0)
	s_waitcnt vmcnt(0) lgkmcnt(0)
	s_barrier
	v_readlane_b32 s100, v249, 18
	s_nop 3
	s_cmp_eq_u32 s100, 0
	s_cbranch_scc1 .Lwarm_done_5
	s_lshr_b32 s101, s92, 9
	s_and_b32 s101, s101, 3
	s_mul_i32 s101, s101, 0x80000
	s_add_u32 s98, s28, 0x5600000
	s_addc_u32 s99, s29, 0
	s_add_u32 s98, s98, s101
	s_addc_u32 s99, s99, 0
	v_lshrrev_b32_e32 v250, 1, v196
	v_lshl_add_u32 v250, s100, 5, v250
	v_mul_u32_u24_e32 v250, 0x800, v250
	v_and_b32_e32 v251, 1, v196
	v_lshl_add_u32 v250, v251, 7, v250
	global_load_dword v250, v250, s[98:99]

; __device__ __forceinline__ void xcd_barrier(const XcdBarrier& b) {
;     asm volatile("s_waitcnt vmcnt(0)" ::: "memory");
;     __syncthreads();
.LBB0_1747:
	s_cmp_gt_i32 s31, 17
	s_cselect_b64 s[0:1], -1, 0
	s_and_b64 s[4:5], s[6:7], s[0:1]
	s_andn2_b64 vcc, exec, s[4:5]
	s_cbranch_vccnz .LBB0_1801
	s_waitcnt vmcnt(0)
	s_waitcnt vmcnt(0) lgkmcnt(0)
	s_barrier
	v_readlane_b32 s100, v249, 18
	s_nop 3
	s_cmp_eq_u32 s100, 0
	s_cbranch_scc1 .Lwarm_done_6
	s_lshr_b32 s101, s92, 9
	s_and_b32 s101, s101, 3
	s_mul_i32 s101, s101, 0x160000
	s_add_u32 s98, s28, 0x4480000
	s_addc_u32 s99, s29, 0
	s_add_u32 s98, s98, s101
	s_addc_u32 s99, s99, 0
	v_lshrrev_b32_e32 v250, 1, v196
	v_lshl_add_u32 v250, s100, 5, v250
	v_mul_u32_u24_e32 v250, 0x1600, v250
	v_and_b32_e32 v251, 1, v196
	v_lshl_add_u32 v250, v251, 7, v250
	global_load_dword v250, v250, s[98:99]
